# attention unit tails: the four dependent LDS read round trips of the cross-head row-sum exchange issued together (same summation order)
# speedup vs baseline: 1.0032x; 1.0032x over previous
.LBB0_606:
	s_or_b64 exec, exec, s[12:13]
	v_add_u32_e32 v166, 0xf000, v184
	s_waitcnt lgkmcnt(0)
	s_barrier
	ds_read2_b32 v[28:29], v166 offset1:32
	ds_read2_b32 v[50:51], v166 offset0:64 offset1:96
	ds_read2_b32 v[52:53], v166 offset0:128 offset1:160
	ds_read2_b32 v[54:55], v166 offset0:192 offset1:224
	s_waitcnt lgkmcnt(0)
	v_add_f32_e32 v0, 0, v28
	v_add_f32_e32 v0, v0, v29
	v_add_f32_e32 v0, v0, v50
	v_add_f32_e32 v0, v0, v51
	v_add_f32_e32 v0, v0, v52
	v_add_f32_e32 v0, v0, v53
	v_add_f32_e32 v0, v0, v54
	v_add_f32_e32 v0, v0, v55
	s_add_i32 s22, s22, s96
	v_or_b32_e32 v28, s10, v174
	v_ashrrev_i32_e32 v29, 31, v28
	v_lshlrev_b64 v[36:37], 11, v[28:29]
	v_fmamk_f32 v0, v0, 0x3b000000, v231
	v_rsq_f32_e32 v0, v0
	v_readlane_b32 s10, v252, 55
	s_add_i32 s21, s21, s10
	s_cmpk_gt_i32 s22, 0xff
	v_pk_mul_f32 v[38:39], v[48:49], v[0:1] op_sel_hi:[1,0]
	v_pk_mul_f32 v[34:35], v[34:35], v[0:1] op_sel_hi:[1,0]
	v_pk_mul_f32 v[18:19], v[18:19], v[0:1] op_sel_hi:[1,0]
	v_pk_mul_f32 v[22:23], v[22:23], v[0:1] op_sel_hi:[1,0]
	v_pk_mul_f32 v[8:9], v[8:9], v[0:1] op_sel_hi:[1,0]
	v_pk_mul_f32 v[10:11], v[10:11], v[0:1] op_sel_hi:[1,0]
	v_pk_mul_f32 v[2:3], v[2:3], v[0:1] op_sel_hi:[1,0]
	v_pk_mul_f32 v[6:7], v[6:7], v[0:1] op_sel_hi:[1,0]
	s_waitcnt vmcnt(0)
	v_pk_mul_f32 v[28:29], v[64:65], v[38:39]
	v_pk_mul_f32 v[30:31], v[66:67], v[34:35]
	v_cvt_pk_bf16_f32 v28, v28, v29
	v_cvt_pk_bf16_f32 v29, v30, v31
	v_lshl_add_u64 v[34:35], v[144:145], 0, v[36:37]
	global_store_dwordx2 v[34:35], v[28:29], off offset:512
	v_pk_mul_f32 v[18:19], v[68:69], v[18:19]
	v_pk_mul_f32 v[28:29], v[32:33], v[0:1] op_sel_hi:[1,0]
	v_cvt_pk_bf16_f32 v18, v18, v19
	v_pk_mul_f32 v[28:29], v[70:71], v[28:29]
	s_nop 0
	v_cvt_pk_bf16_f32 v19, v28, v29
	global_store_dwordx2 v[34:35], v[18:19], off offset:528
	v_pk_mul_f32 v[18:19], v[20:21], v[0:1] op_sel_hi:[1,0]
	v_pk_mul_f32 v[20:21], v[24:25], v[0:1] op_sel_hi:[1,0]
	v_pk_mul_f32 v[18:19], v[18:19], v[72:73]
	v_pk_mul_f32 v[20:21], v[20:21], v[74:75]
	v_cvt_pk_bf16_f32 v18, v18, v19
	v_cvt_pk_bf16_f32 v19, v20, v21
	global_store_dwordx2 v[34:35], v[18:19], off offset:544
	v_pk_mul_f32 v[18:19], v[22:23], v[76:77]
	v_pk_mul_f32 v[22:23], v[26:27], v[0:1] op_sel_hi:[1,0]
	v_cvt_pk_bf16_f32 v18, v18, v19
	v_pk_mul_f32 v[20:21], v[22:23], v[78:79]
	s_nop 0
	v_cvt_pk_bf16_f32 v19, v20, v21
	global_store_dwordx2 v[34:35], v[18:19], off offset:560
	v_pk_mul_f32 v[8:9], v[8:9], v[116:117]
	v_pk_mul_f32 v[10:11], v[10:11], v[118:119]
	v_cvt_pk_bf16_f32 v8, v8, v9
	v_cvt_pk_bf16_f32 v9, v10, v11
	global_store_dwordx2 v[34:35], v[8:9], off offset:576
	v_pk_mul_f32 v[2:3], v[2:3], v[120:121]
	v_pk_mul_f32 v[8:9], v[12:13], v[0:1] op_sel_hi:[1,0]
	v_cvt_pk_bf16_f32 v2, v2, v3
	v_pk_mul_f32 v[8:9], v[8:9], v[122:123]
	s_nop 0
	v_cvt_pk_bf16_f32 v3, v8, v9
	global_store_dwordx2 v[34:35], v[2:3], off offset:592
	v_pk_mul_f32 v[2:3], v[4:5], v[0:1] op_sel_hi:[1,0]
	v_pk_mul_f32 v[4:5], v[14:15], v[0:1] op_sel_hi:[1,0]
	v_pk_mul_f32 v[2:3], v[2:3], v[124:125]
	v_pk_mul_f32 v[4:5], v[4:5], v[126:127]
	v_cvt_pk_bf16_f32 v2, v2, v3
	v_cvt_pk_bf16_f32 v3, v4, v5
	global_store_dwordx2 v[34:35], v[2:3], off offset:608
	v_pk_mul_f32 v[2:3], v[6:7], v[128:129]
	v_pk_mul_f32 v[6:7], v[16:17], v[0:1] op_sel_hi:[1,0]
	v_cvt_pk_bf16_f32 v2, v2, v3
	v_pk_mul_f32 v[4:5], v[6:7], v[130:131]
	s_nop 0
	v_cvt_pk_bf16_f32 v3, v4, v5
	global_store_dwordx2 v[34:35], v[2:3], off offset:624
	s_barrier
	s_cbranch_scc1 .LBB0_627

.LBB0_628:
	s_or_b64 exec, exec, s[10:11]
	s_waitcnt lgkmcnt(0)
	s_barrier
	ds_read2_b32 v[28:29], v166 offset1:32
	ds_read2_b32 v[50:51], v166 offset0:64 offset1:96
	ds_read2_b32 v[52:53], v166 offset0:128 offset1:160
	ds_read2_b32 v[54:55], v166 offset0:192 offset1:224
	s_waitcnt lgkmcnt(0)
	v_add_f32_e32 v0, 0, v28
	v_add_f32_e32 v0, v0, v29
	v_add_f32_e32 v0, v0, v50
	v_add_f32_e32 v0, v0, v51
	v_add_f32_e32 v0, v0, v52
	v_add_f32_e32 v0, v0, v53
	v_add_f32_e32 v0, v0, v54
	v_add_f32_e32 v0, v0, v55
	s_add_i32 s16, s16, s96
	v_or_b32_e32 v28, s8, v174
	v_ashrrev_i32_e32 v29, 31, v28
	v_lshlrev_b64 v[36:37], 11, v[28:29]
	v_fmamk_f32 v0, v0, 0x3b000000, v231
	v_rsq_f32_e32 v0, v0
	v_readlane_b32 s8, v252, 55
	s_add_i32 s17, s17, s8
	s_cmpk_gt_i32 s16, 0xff
	v_pk_mul_f32 v[38:39], v[48:49], v[0:1] op_sel_hi:[1,0]
	v_pk_mul_f32 v[34:35], v[34:35], v[0:1] op_sel_hi:[1,0]
	v_pk_mul_f32 v[18:19], v[18:19], v[0:1] op_sel_hi:[1,0]
	v_pk_mul_f32 v[22:23], v[22:23], v[0:1] op_sel_hi:[1,0]
	v_pk_mul_f32 v[8:9], v[8:9], v[0:1] op_sel_hi:[1,0]
	v_pk_mul_f32 v[10:11], v[10:11], v[0:1] op_sel_hi:[1,0]
	v_pk_mul_f32 v[2:3], v[2:3], v[0:1] op_sel_hi:[1,0]
	v_pk_mul_f32 v[6:7], v[6:7], v[0:1] op_sel_hi:[1,0]
	s_waitcnt vmcnt(0)
	v_pk_mul_f32 v[28:29], v[64:65], v[38:39]
	v_pk_mul_f32 v[30:31], v[66:67], v[34:35]
	v_cvt_pk_bf16_f32 v28, v28, v29
	v_cvt_pk_bf16_f32 v29, v30, v31
	v_lshl_add_u64 v[34:35], v[144:145], 0, v[36:37]
	global_store_dwordx2 v[34:35], v[28:29], off offset:512
	v_pk_mul_f32 v[18:19], v[68:69], v[18:19]
	v_pk_mul_f32 v[28:29], v[32:33], v[0:1] op_sel_hi:[1,0]
	v_cvt_pk_bf16_f32 v18, v18, v19
	v_pk_mul_f32 v[28:29], v[70:71], v[28:29]
	s_nop 0
	v_cvt_pk_bf16_f32 v19, v28, v29
	global_store_dwordx2 v[34:35], v[18:19], off offset:528
	v_pk_mul_f32 v[18:19], v[20:21], v[0:1] op_sel_hi:[1,0]
	v_pk_mul_f32 v[20:21], v[24:25], v[0:1] op_sel_hi:[1,0]
	v_pk_mul_f32 v[18:19], v[18:19], v[72:73]
	v_pk_mul_f32 v[20:21], v[20:21], v[74:75]
	v_cvt_pk_bf16_f32 v18, v18, v19
	v_cvt_pk_bf16_f32 v19, v20, v21
	global_store_dwordx2 v[34:35], v[18:19], off offset:544
	v_pk_mul_f32 v[18:19], v[22:23], v[76:77]
	v_pk_mul_f32 v[22:23], v[26:27], v[0:1] op_sel_hi:[1,0]
	v_cvt_pk_bf16_f32 v18, v18, v19
	v_pk_mul_f32 v[20:21], v[22:23], v[78:79]
	s_nop 0
	v_cvt_pk_bf16_f32 v19, v20, v21
	global_store_dwordx2 v[34:35], v[18:19], off offset:560
	v_pk_mul_f32 v[8:9], v[8:9], v[116:117]
	v_pk_mul_f32 v[10:11], v[10:11], v[118:119]
	v_cvt_pk_bf16_f32 v8, v8, v9
	v_cvt_pk_bf16_f32 v9, v10, v11
	global_store_dwordx2 v[34:35], v[8:9], off offset:576
	v_pk_mul_f32 v[2:3], v[2:3], v[120:121]
	v_pk_mul_f32 v[8:9], v[12:13], v[0:1] op_sel_hi:[1,0]
	v_cvt_pk_bf16_f32 v2, v2, v3
	v_pk_mul_f32 v[8:9], v[8:9], v[122:123]
	s_nop 0
	v_cvt_pk_bf16_f32 v3, v8, v9
	global_store_dwordx2 v[34:35], v[2:3], off offset:592
	v_pk_mul_f32 v[2:3], v[4:5], v[0:1] op_sel_hi:[1,0]
	v_pk_mul_f32 v[4:5], v[14:15], v[0:1] op_sel_hi:[1,0]
	v_pk_mul_f32 v[2:3], v[2:3], v[124:125]
	v_pk_mul_f32 v[4:5], v[4:5], v[126:127]
	v_cvt_pk_bf16_f32 v2, v2, v3
	v_cvt_pk_bf16_f32 v3, v4, v5
	global_store_dwordx2 v[34:35], v[2:3], off offset:608
	v_pk_mul_f32 v[2:3], v[6:7], v[128:129]
	v_pk_mul_f32 v[6:7], v[16:17], v[0:1] op_sel_hi:[1,0]
	v_cvt_pk_bf16_f32 v2, v2, v3
	v_pk_mul_f32 v[4:5], v[6:7], v[130:131]
	s_nop 0
	v_cvt_pk_bf16_f32 v3, v4, v5
	global_store_dwordx2 v[34:35], v[2:3], off offset:624
	s_barrier
	s_cbranch_scc1 .LBB0_637
